# phase 0: hand-written weight conversion (16B loads, no LDS transpose, 3 items of loads in flight per wave)
# speedup vs baseline: 1.0123x; 1.0030x over previous
.LBB0_1368:
	s_andn2_b64 vcc, exec, s[0:1]
	s_cbranch_vccnz .LBB0_1493
	v_readlane_b32 s0, v252, 26
	v_writelane_b32 v253, s60, 0
	v_readlane_b32 s1, v252, 27
	s_lshl_b32 s0, s0, 3
	v_writelane_b32 v253, s61, 1
	v_readlane_b32 s1, v252, 28
	v_writelane_b32 v253, s62, 2
	s_add_i32 s42, s1, s0
	s_lshl_b32 s76, s58, 3
	v_writelane_b32 v253, s63, 3
	s_mov_b32 s84, s58
	s_cmpk_gt_i32 s42, 0x32af
	s_cbranch_scc1 .LBB0_1472
	v_readlane_b32 s4, v252, 24
	v_readlane_b32 s5, v252, 25
	v_readlane_b32 s8, v252, 29
	s_load_dwordx2 s[6:7], s[4:5], 0xb8
	v_and_b32_e32 v124, 63, v186
	v_and_b32_e32 v120, 7, v124
	v_lshrrev_b32_e32 v121, 3, v124
	v_lshlrev_b32_e32 v122, 4, v120
	v_lshlrev_b32_e32 v123, 4, v121
	s_mov_b32 s0, s42
	s_mov_b32 s2, 0
	s_mov_b32 s3, 0
	s_waitcnt lgkmcnt(0)
	s_cmp_lt_u32 s0, 12976
	s_cbranch_scc0 .Lcv_loop0
	s_cmp_lt_u32 s0, 1408
	s_cbranch_scc1 .Lcv_b0_m0
	s_cmp_lt_u32 s0, 2816
	s_cbranch_scc1 .Lcv_b0_m1
	s_cmp_lt_u32 s0, 4224
	s_cbranch_scc1 .Lcv_b0_m2
	s_cmp_lt_u32 s0, 7088
	s_cbranch_scc1 .Lcv_b0_m3
	s_cmp_lt_u32 s0, 7344
	s_cbranch_scc1 .Lcv_b0_m4
	s_cmp_lt_u32 s0, 7600
	s_cbranch_scc1 .Lcv_b0_m5
	s_cmp_lt_u32 s0, 8112
	s_cbranch_scc1 .Lcv_b0_m6
	s_cmp_lt_u32 s0, 9520
	s_cbranch_scc1 .Lcv_b0_m7
	s_cmp_lt_u32 s0, 10928
	s_cbranch_scc1 .Lcv_b0_m8
	s_cmp_lt_u32 s0, 12336
	s_cbranch_scc1 .Lcv_b0_m9
	s_cmp_lt_u32 s0, 12848
	s_cbranch_scc1 .Lcv_b0_m10
	s_movk_i32 s9, 0x100
	s_movk_i32 s10, 0x400
	s_movk_i32 s11, 32
	s_mov_b32 s12, 32768
	s_movk_i32 s13, 0x98
	s_mov_b32 s14, 0x100000
	s_mov_b32 s15, 0x3280000
	s_mov_b32 s16, 0
	s_movk_i32 s17, 12848
	s_branch .Lcv_b0_common
.Lcv_b0_m10:
	s_movk_i32 s9, 0x400
	s_movk_i32 s10, 0x400
	s_movk_i32 s11, 32
	s_mov_b32 s12, 32768
	s_movk_i32 s13, 0xa0
	s_mov_b32 s14, 0x400000
	s_mov_b32 s15, 0x3080000
	s_mov_b32 s16, 0
	s_movk_i32 s17, 12336
	s_branch .Lcv_b0_common
.Lcv_b0_m9:
	s_movk_i32 s9, 0xb00
	s_movk_i32 s10, 0x400
	s_movk_i32 s11, 32
	s_mov_b32 s12, 32768
	s_movk_i32 s13, 0x90
	s_mov_b32 s14, 0xb00000
	s_mov_b32 s15, 0x2b00000
	s_mov_b32 s16, 0
	s_movk_i32 s17, 10928
	s_branch .Lcv_b0_common
.Lcv_b0_m8:
	s_movk_i32 s9, 0x400
	s_movk_i32 s10, 0xb00
	s_movk_i32 s11, 88
	s_mov_b32 s12, 11916
	s_movk_i32 s13, 0x88
	s_mov_b32 s14, 0xb00000
	s_mov_b32 s15, 0x2000000
	s_mov_b32 s16, 2
	s_movk_i32 s17, 9520
	s_branch .Lcv_b0_common
.Lcv_b0_m7:
	s_movk_i32 s9, 0x400
	s_movk_i32 s10, 0xb00
	s_movk_i32 s11, 88
	s_mov_b32 s12, 11916
	s_movk_i32 s13, 0x80
	s_mov_b32 s14, 0xb00000
	s_mov_b32 s15, 0x2000000
	s_mov_b32 s16, 1
	s_movk_i32 s17, 8112
	s_branch .Lcv_b0_common
.Lcv_b0_m6:
	s_movk_i32 s9, 0x400
	s_movk_i32 s10, 0x400
	s_movk_i32 s11, 32
	s_mov_b32 s12, 32768
	s_movk_i32 s13, 0x40
	s_mov_b32 s14, 0x400000
	s_mov_b32 s15, 0x1e00000
	s_mov_b32 s16, 0
	s_movk_i32 s17, 7600
	s_branch .Lcv_b0_common
.Lcv_b0_m5:
	s_movk_i32 s9, 0x200
	s_movk_i32 s10, 0x400
	s_movk_i32 s11, 32
	s_mov_b32 s12, 32768
	s_movk_i32 s13, 0x38
	s_mov_b32 s14, 0x200000
	s_mov_b32 s15, 0x1d00000
	s_mov_b32 s16, 0
	s_movk_i32 s17, 7344
	s_branch .Lcv_b0_common
.Lcv_b0_m4:
	s_movk_i32 s9, 0x200
	s_movk_i32 s10, 0x400
	s_movk_i32 s11, 32
	s_mov_b32 s12, 32768
	s_movk_i32 s13, 0x30
	s_mov_b32 s14, 0x200000
	s_mov_b32 s15, 0x1c00000
	s_mov_b32 s16, 0
	s_movk_i32 s17, 7088
	s_branch .Lcv_b0_common
.Lcv_b0_m3:
	s_movk_i32 s9, 0x400
	s_movk_i32 s10, 0x1658
	s_movk_i32 s11, 179
	s_mov_b32 s12, 5858
	s_movk_i32 s13, 0x10
	s_mov_b32 s14, 0x1658000
	s_mov_b32 s15, 0x1080000
	s_mov_b32 s16, 0
	s_movk_i32 s17, 4224
	s_branch .Lcv_b0_common
.Lcv_b0_m2:
	s_movk_i32 s9, 0xb00
	s_movk_i32 s10, 0x400
	s_movk_i32 s11, 32
	s_mov_b32 s12, 32768
	s_movk_i32 s13, 0x78
	s_mov_b32 s14, 0xb00000
	s_mov_b32 s15, 0xb00000
	s_mov_b32 s16, 0
	s_movk_i32 s17, 2816
	s_branch .Lcv_b0_common
.Lcv_b0_m1:
	s_movk_i32 s9, 0x400
	s_movk_i32 s10, 0xb00
	s_movk_i32 s11, 88
	s_mov_b32 s12, 11916
	s_movk_i32 s13, 0x70
	s_mov_b32 s14, 0xb00000
	s_mov_b32 s15, 0x0
	s_mov_b32 s16, 2
	s_movk_i32 s17, 1408
	s_branch .Lcv_b0_common
.Lcv_b0_m0:
	s_movk_i32 s9, 0x400
	s_movk_i32 s10, 0xb00
	s_movk_i32 s11, 88
	s_mov_b32 s12, 11916
	s_movk_i32 s13, 0x68
	s_mov_b32 s14, 0xb00000
	s_mov_b32 s15, 0x0
	s_mov_b32 s16, 1
	s_movk_i32 s17, 0
.Lcv_b0_common:
	s_sub_u32 s17, s0, s17
	s_load_dwordx2 s[20:21], s[4:5], s13
	s_mul_i32 s18, s17, s12
	s_lshr_b32 s18, s18, 20
	s_mul_i32 s19, s18, s11
	s_sub_u32 s19, s17, s19
	s_lshl_b32 s22, s19, 5
	s_sub_u32 s23, s10, s22
	s_lshr_b32 s23, s23, 2
	s_min_u32 s23, s23, 8
	v_cmp_gt_u32_e64 s[38:39], s23, v120
	s_mul_i32 s24, s18, s10
	s_lshl_b32 s24, s24, 6
	s_add_u32 s24, s24, s22
	s_lshl_b32 s24, s24, 2
	s_mul_i32 s25, s8, s14
	s_add_u32 s24, s24, s25
	s_lshl_b32 s25, s10, 5
	v_mad_u32_u24 v124, v121, s25, v122
	s_lshl_b32 s25, s10, 2
	s_waitcnt lgkmcnt(0)
	s_add_u32 s20, s20, s24
	s_addc_u32 s21, s21, 0
	s_mov_b64 exec, s[38:39]
	global_load_dwordx4 v[0:3], v124, s[20:21]
	s_add_u32 s20, s20, s25
	s_addc_u32 s21, s21, 0
	global_load_dwordx4 v[4:7], v124, s[20:21]
	s_add_u32 s20, s20, s25
	s_addc_u32 s21, s21, 0
	global_load_dwordx4 v[8:11], v124, s[20:21]
	s_add_u32 s20, s20, s25
	s_addc_u32 s21, s21, 0
	global_load_dwordx4 v[12:15], v124, s[20:21]
	s_add_u32 s20, s20, s25
	s_addc_u32 s21, s21, 0
	global_load_dwordx4 v[16:19], v124, s[20:21]
	s_add_u32 s20, s20, s25
	s_addc_u32 s21, s21, 0
	global_load_dwordx4 v[20:23], v124, s[20:21]
	s_add_u32 s20, s20, s25
	s_addc_u32 s21, s21, 0
	global_load_dwordx4 v[24:27], v124, s[20:21]
	s_add_u32 s20, s20, s25
	s_addc_u32 s21, s21, 0
	global_load_dwordx4 v[28:31], v124, s[20:21]
	s_mov_b64 exec, -1
	s_lshr_b32 s23, s22, 7
	s_lshl_b32 s23, s23, 8
	s_and_b32 s25, s22, 0x7f
	s_add_u32 s23, s23, s25
	s_cmp_eq_u32 s16, 0
	s_cselect_b32 s23, s22, s23
	s_cmp_eq_u32 s16, 2
	s_cselect_b32 s25, 0x80, 0
	s_add_u32 s23, s23, s25
	s_mul_i32 s23, s23, s9
	s_lshl_b32 s25, s18, 6
	s_add_u32 s23, s23, s25
	s_lshl_b32 s23, s23, 1
	s_add_u32 s23, s23, s15
	s_add_u32 s46, s6, s23
	s_addc_u32 s47, s7, 0
	s_lshl_b32 s52, s9, 1
	s_lshl_b32 s25, s9, 3
	v_mad_u32_u24 v125, v120, s25, v123
	s_add_u32 s0, s0, s76
	s_add_u32 s3, s3, 1
	s_cmp_lt_u32 s0, 12976
	s_cbranch_scc0 .Lcv_loop0
	s_cmp_lt_u32 s0, 1408
	s_cbranch_scc1 .Lcv_b1_m0
	s_cmp_lt_u32 s0, 2816
	s_cbranch_scc1 .Lcv_b1_m1
	s_cmp_lt_u32 s0, 4224
	s_cbranch_scc1 .Lcv_b1_m2
	s_cmp_lt_u32 s0, 7088
	s_cbranch_scc1 .Lcv_b1_m3
	s_cmp_lt_u32 s0, 7344
	s_cbranch_scc1 .Lcv_b1_m4
	s_cmp_lt_u32 s0, 7600
	s_cbranch_scc1 .Lcv_b1_m5
	s_cmp_lt_u32 s0, 8112
	s_cbranch_scc1 .Lcv_b1_m6
	s_cmp_lt_u32 s0, 9520
	s_cbranch_scc1 .Lcv_b1_m7
	s_cmp_lt_u32 s0, 10928
	s_cbranch_scc1 .Lcv_b1_m8
	s_cmp_lt_u32 s0, 12336
	s_cbranch_scc1 .Lcv_b1_m9
	s_cmp_lt_u32 s0, 12848
	s_cbranch_scc1 .Lcv_b1_m10
	s_movk_i32 s9, 0x100
	s_movk_i32 s10, 0x400
	s_movk_i32 s11, 32
	s_mov_b32 s12, 32768
	s_movk_i32 s13, 0x98
	s_mov_b32 s14, 0x100000
	s_mov_b32 s15, 0x3280000
	s_mov_b32 s16, 0
	s_movk_i32 s17, 12848
	s_branch .Lcv_b1_common

.Lcv_b1_common:
	s_sub_u32 s17, s0, s17
	s_load_dwordx2 s[20:21], s[4:5], s13
	s_mul_i32 s18, s17, s12
	s_lshr_b32 s18, s18, 20
	s_mul_i32 s19, s18, s11
	s_sub_u32 s19, s17, s19
	s_lshl_b32 s22, s19, 5
	s_sub_u32 s23, s10, s22
	s_lshr_b32 s23, s23, 2
	s_min_u32 s23, s23, 8
	v_cmp_gt_u32_e64 s[40:41], s23, v120
	s_mul_i32 s24, s18, s10
	s_lshl_b32 s24, s24, 6
	s_add_u32 s24, s24, s22
	s_lshl_b32 s24, s24, 2
	s_mul_i32 s25, s8, s14
	s_add_u32 s24, s24, s25
	s_lshl_b32 s25, s10, 5
	v_mad_u32_u24 v124, v121, s25, v122
	s_lshl_b32 s25, s10, 2
	s_waitcnt lgkmcnt(0)
	s_add_u32 s20, s20, s24
	s_addc_u32 s21, s21, 0
	s_mov_b64 exec, s[40:41]
	global_load_dwordx4 v[34:37], v124, s[20:21]
	s_add_u32 s20, s20, s25
	s_addc_u32 s21, s21, 0
	global_load_dwordx4 v[38:41], v124, s[20:21]
	s_add_u32 s20, s20, s25
	s_addc_u32 s21, s21, 0
	global_load_dwordx4 v[42:45], v124, s[20:21]
	s_add_u32 s20, s20, s25
	s_addc_u32 s21, s21, 0
	global_load_dwordx4 v[46:49], v124, s[20:21]
	s_add_u32 s20, s20, s25
	s_addc_u32 s21, s21, 0
	global_load_dwordx4 v[50:53], v124, s[20:21]
	s_add_u32 s20, s20, s25
	s_addc_u32 s21, s21, 0
	global_load_dwordx4 v[54:57], v124, s[20:21]
	s_add_u32 s20, s20, s25
	s_addc_u32 s21, s21, 0
	global_load_dwordx4 v[58:61], v124, s[20:21]
	s_add_u32 s20, s20, s25
	s_addc_u32 s21, s21, 0
	global_load_dwordx4 v[62:65], v124, s[20:21]
	s_mov_b64 exec, -1
	s_lshr_b32 s23, s22, 7
	s_lshl_b32 s23, s23, 8
	s_and_b32 s25, s22, 0x7f
	s_add_u32 s23, s23, s25
	s_cmp_eq_u32 s16, 0
	s_cselect_b32 s23, s22, s23
	s_cmp_eq_u32 s16, 2
	s_cselect_b32 s25, 0x80, 0
	s_add_u32 s23, s23, s25
	s_mul_i32 s23, s23, s9
	s_lshl_b32 s25, s18, 6
	s_add_u32 s23, s23, s25
	s_lshl_b32 s23, s23, 1
	s_add_u32 s23, s23, s15
	s_add_u32 s48, s6, s23
	s_addc_u32 s49, s7, 0
	s_lshl_b32 s53, s9, 1
	s_lshl_b32 s25, s9, 3
	v_mad_u32_u24 v126, v120, s25, v123
	s_add_u32 s0, s0, s76
	s_add_u32 s3, s3, 1
	s_cmp_lt_u32 s0, 12976
	s_cbranch_scc0 .Lcv_loop0
	s_cmp_lt_u32 s0, 1408
	s_cbranch_scc1 .Lcv_b2_m0
	s_cmp_lt_u32 s0, 2816
	s_cbranch_scc1 .Lcv_b2_m1
	s_cmp_lt_u32 s0, 4224
	s_cbranch_scc1 .Lcv_b2_m2
	s_cmp_lt_u32 s0, 7088
	s_cbranch_scc1 .Lcv_b2_m3
	s_cmp_lt_u32 s0, 7344
	s_cbranch_scc1 .Lcv_b2_m4
	s_cmp_lt_u32 s0, 7600
	s_cbranch_scc1 .Lcv_b2_m5
	s_cmp_lt_u32 s0, 8112
	s_cbranch_scc1 .Lcv_b2_m6
	s_cmp_lt_u32 s0, 9520
	s_cbranch_scc1 .Lcv_b2_m7
	s_cmp_lt_u32 s0, 10928
	s_cbranch_scc1 .Lcv_b2_m8
	s_cmp_lt_u32 s0, 12336
	s_cbranch_scc1 .Lcv_b2_m9
	s_cmp_lt_u32 s0, 12848
	s_cbranch_scc1 .Lcv_b2_m10
	s_movk_i32 s9, 0x100
	s_movk_i32 s10, 0x400
	s_movk_i32 s11, 32
	s_mov_b32 s12, 32768
	s_movk_i32 s13, 0x98
	s_mov_b32 s14, 0x100000
	s_mov_b32 s15, 0x3280000
	s_mov_b32 s16, 0
	s_movk_i32 s17, 12848
	s_branch .Lcv_b2_common

.Lcv_b2_common:
	s_sub_u32 s17, s0, s17
	s_load_dwordx2 s[20:21], s[4:5], s13
	s_mul_i32 s18, s17, s12
	s_lshr_b32 s18, s18, 20
	s_mul_i32 s19, s18, s11
	s_sub_u32 s19, s17, s19
	s_lshl_b32 s22, s19, 5
	s_sub_u32 s23, s10, s22
	s_lshr_b32 s23, s23, 2
	s_min_u32 s23, s23, 8
	v_cmp_gt_u32_e64 s[44:45], s23, v120
	s_mul_i32 s24, s18, s10
	s_lshl_b32 s24, s24, 6
	s_add_u32 s24, s24, s22
	s_lshl_b32 s24, s24, 2
	s_mul_i32 s25, s8, s14
	s_add_u32 s24, s24, s25
	s_lshl_b32 s25, s10, 5
	v_mad_u32_u24 v124, v121, s25, v122
	s_lshl_b32 s25, s10, 2
	s_waitcnt lgkmcnt(0)
	s_add_u32 s20, s20, s24
	s_addc_u32 s21, s21, 0
	s_mov_b64 exec, s[44:45]
	global_load_dwordx4 v[70:73], v124, s[20:21]
	s_add_u32 s20, s20, s25
	s_addc_u32 s21, s21, 0
	global_load_dwordx4 v[74:77], v124, s[20:21]
	s_add_u32 s20, s20, s25
	s_addc_u32 s21, s21, 0
	global_load_dwordx4 v[78:81], v124, s[20:21]
	s_add_u32 s20, s20, s25
	s_addc_u32 s21, s21, 0
	global_load_dwordx4 v[82:85], v124, s[20:21]
	s_add_u32 s20, s20, s25
	s_addc_u32 s21, s21, 0
	global_load_dwordx4 v[86:89], v124, s[20:21]
	s_add_u32 s20, s20, s25
	s_addc_u32 s21, s21, 0
	global_load_dwordx4 v[90:93], v124, s[20:21]
	s_add_u32 s20, s20, s25
	s_addc_u32 s21, s21, 0
	global_load_dwordx4 v[94:97], v124, s[20:21]
	s_add_u32 s20, s20, s25
	s_addc_u32 s21, s21, 0
	global_load_dwordx4 v[98:101], v124, s[20:21]
	s_mov_b64 exec, -1
	s_lshr_b32 s23, s22, 7
	s_lshl_b32 s23, s23, 8
	s_and_b32 s25, s22, 0x7f
	s_add_u32 s23, s23, s25
	s_cmp_eq_u32 s16, 0
	s_cselect_b32 s23, s22, s23
	s_cmp_eq_u32 s16, 2
	s_cselect_b32 s25, 0x80, 0
	s_add_u32 s23, s23, s25
	s_mul_i32 s23, s23, s9
	s_lshl_b32 s25, s18, 6
	s_add_u32 s23, s23, s25
	s_lshl_b32 s23, s23, 1
	s_add_u32 s23, s23, s15
	s_add_u32 s50, s6, s23
	s_addc_u32 s51, s7, 0
	s_lshl_b32 s54, s9, 1
	s_lshl_b32 s25, s9, 3
	v_mad_u32_u24 v127, v120, s25, v123
	s_add_u32 s0, s0, s76
	s_add_u32 s3, s3, 1
.Lcv_loop0:
	s_cmp_eq_u32 s3, 0
	s_cbranch_scc1 .Lcv_done
	s_min_u32 s22, s2, 2
	s_lshl_b32 s22, s22, 2
	s_sub_u32 s23, s3, 1
	s_lshl_b32 s23, s23, 3
	s_add_u32 s22, s22, s23
	s_cmp_eq_u32 s22, 24
	s_cbranch_scc1 .Lcv_l0_w24
	s_cmp_eq_u32 s22, 20
	s_cbranch_scc1 .Lcv_l0_w20
	s_cmp_eq_u32 s22, 16
	s_cbranch_scc1 .Lcv_l0_w16
	s_cmp_eq_u32 s22, 12
	s_cbranch_scc1 .Lcv_l0_w12
	s_cmp_eq_u32 s22, 8
	s_cbranch_scc1 .Lcv_l0_w8
	s_cmp_eq_u32 s22, 4
	s_cbranch_scc1 .Lcv_l0_w4
	s_waitcnt vmcnt(0)
	s_branch .Lcv_l0_wd
.Lcv_l0_w24:
	s_waitcnt vmcnt(24)
	s_branch .Lcv_l0_wd
.Lcv_l0_w20:
	s_waitcnt vmcnt(20)
	s_branch .Lcv_l0_wd
.Lcv_l0_w16:
	s_waitcnt vmcnt(16)
	s_branch .Lcv_l0_wd
.Lcv_l0_w12:
	s_waitcnt vmcnt(12)
	s_branch .Lcv_l0_wd
.Lcv_l0_w8:
	s_waitcnt vmcnt(8)
	s_branch .Lcv_l0_wd
.Lcv_l0_w4:
	s_waitcnt vmcnt(4)
.Lcv_l0_wd:
	s_mov_b64 exec, s[38:39]
	v_cvt_pk_bf16_f32 v104, v0, v4
	v_cvt_pk_bf16_f32 v105, v8, v12
	v_cvt_pk_bf16_f32 v106, v16, v20
	v_cvt_pk_bf16_f32 v107, v24, v28
	global_store_dwordx4 v125, v[104:107], s[46:47]
	s_add_u32 s46, s46, s52
	s_addc_u32 s47, s47, 0
	v_cvt_pk_bf16_f32 v108, v1, v5
	v_cvt_pk_bf16_f32 v109, v9, v13
	v_cvt_pk_bf16_f32 v110, v17, v21
	v_cvt_pk_bf16_f32 v111, v25, v29
	global_store_dwordx4 v125, v[108:111], s[46:47]
	s_add_u32 s46, s46, s52
	s_addc_u32 s47, s47, 0
	v_cvt_pk_bf16_f32 v104, v2, v6
	v_cvt_pk_bf16_f32 v105, v10, v14
	v_cvt_pk_bf16_f32 v106, v18, v22
	v_cvt_pk_bf16_f32 v107, v26, v30
	global_store_dwordx4 v125, v[104:107], s[46:47]
	s_add_u32 s46, s46, s52
	s_addc_u32 s47, s47, 0
	v_cvt_pk_bf16_f32 v108, v3, v7
	v_cvt_pk_bf16_f32 v109, v11, v15
	v_cvt_pk_bf16_f32 v110, v19, v23
	v_cvt_pk_bf16_f32 v111, v27, v31
	global_store_dwordx4 v125, v[108:111], s[46:47]
	s_mov_b64 exec, -1
	s_add_u32 s2, s2, 1
	s_sub_u32 s3, s3, 1
	s_cmp_lt_u32 s0, 12976
	s_cbranch_scc0 .Lcv_loop1
	s_cmp_lt_u32 s0, 1408
	s_cbranch_scc1 .Lcv_r0_m0
	s_cmp_lt_u32 s0, 2816
	s_cbranch_scc1 .Lcv_r0_m1
	s_cmp_lt_u32 s0, 4224
	s_cbranch_scc1 .Lcv_r0_m2
	s_cmp_lt_u32 s0, 7088
	s_cbranch_scc1 .Lcv_r0_m3
	s_cmp_lt_u32 s0, 7344
	s_cbranch_scc1 .Lcv_r0_m4
	s_cmp_lt_u32 s0, 7600
	s_cbranch_scc1 .Lcv_r0_m5
	s_cmp_lt_u32 s0, 8112
	s_cbranch_scc1 .Lcv_r0_m6
	s_cmp_lt_u32 s0, 9520
	s_cbranch_scc1 .Lcv_r0_m7
	s_cmp_lt_u32 s0, 10928
	s_cbranch_scc1 .Lcv_r0_m8
	s_cmp_lt_u32 s0, 12336
	s_cbranch_scc1 .Lcv_r0_m9
	s_cmp_lt_u32 s0, 12848
	s_cbranch_scc1 .Lcv_r0_m10
	s_movk_i32 s9, 0x100
	s_movk_i32 s10, 0x400
	s_movk_i32 s11, 32
	s_mov_b32 s12, 32768
	s_movk_i32 s13, 0x98
	s_mov_b32 s14, 0x100000
	s_mov_b32 s15, 0x3280000
	s_mov_b32 s16, 0
	s_movk_i32 s17, 12848
	s_branch .Lcv_r0_common

.Lcv_r0_common:
	s_sub_u32 s17, s0, s17
	s_load_dwordx2 s[20:21], s[4:5], s13
	s_mul_i32 s18, s17, s12
	s_lshr_b32 s18, s18, 20
	s_mul_i32 s19, s18, s11
	s_sub_u32 s19, s17, s19
	s_lshl_b32 s22, s19, 5
	s_sub_u32 s23, s10, s22
	s_lshr_b32 s23, s23, 2
	s_min_u32 s23, s23, 8
	v_cmp_gt_u32_e64 s[38:39], s23, v120
	s_mul_i32 s24, s18, s10
	s_lshl_b32 s24, s24, 6
	s_add_u32 s24, s24, s22
	s_lshl_b32 s24, s24, 2
	s_mul_i32 s25, s8, s14
	s_add_u32 s24, s24, s25
	s_lshl_b32 s25, s10, 5
	v_mad_u32_u24 v124, v121, s25, v122
	s_lshl_b32 s25, s10, 2
	s_waitcnt lgkmcnt(0)
	s_add_u32 s20, s20, s24
	s_addc_u32 s21, s21, 0
	s_mov_b64 exec, s[38:39]
	global_load_dwordx4 v[0:3], v124, s[20:21]
	s_add_u32 s20, s20, s25
	s_addc_u32 s21, s21, 0
	global_load_dwordx4 v[4:7], v124, s[20:21]
	s_add_u32 s20, s20, s25
	s_addc_u32 s21, s21, 0
	global_load_dwordx4 v[8:11], v124, s[20:21]
	s_add_u32 s20, s20, s25
	s_addc_u32 s21, s21, 0
	global_load_dwordx4 v[12:15], v124, s[20:21]
	s_add_u32 s20, s20, s25
	s_addc_u32 s21, s21, 0
	global_load_dwordx4 v[16:19], v124, s[20:21]
	s_add_u32 s20, s20, s25
	s_addc_u32 s21, s21, 0
	global_load_dwordx4 v[20:23], v124, s[20:21]
	s_add_u32 s20, s20, s25
	s_addc_u32 s21, s21, 0
	global_load_dwordx4 v[24:27], v124, s[20:21]
	s_add_u32 s20, s20, s25
	s_addc_u32 s21, s21, 0
	global_load_dwordx4 v[28:31], v124, s[20:21]
	s_mov_b64 exec, -1
	s_lshr_b32 s23, s22, 7
	s_lshl_b32 s23, s23, 8
	s_and_b32 s25, s22, 0x7f
	s_add_u32 s23, s23, s25
	s_cmp_eq_u32 s16, 0
	s_cselect_b32 s23, s22, s23
	s_cmp_eq_u32 s16, 2
	s_cselect_b32 s25, 0x80, 0
	s_add_u32 s23, s23, s25
	s_mul_i32 s23, s23, s9
	s_lshl_b32 s25, s18, 6
	s_add_u32 s23, s23, s25
	s_lshl_b32 s23, s23, 1
	s_add_u32 s23, s23, s15
	s_add_u32 s46, s6, s23
	s_addc_u32 s47, s7, 0
	s_lshl_b32 s52, s9, 1
	s_lshl_b32 s25, s9, 3
	v_mad_u32_u24 v125, v120, s25, v123
	s_add_u32 s0, s0, s76
	s_add_u32 s3, s3, 1
	s_branch .Lcv_loop1

.Lcv_l1_wd:
	s_mov_b64 exec, s[40:41]
	v_cvt_pk_bf16_f32 v104, v34, v38
	v_cvt_pk_bf16_f32 v105, v42, v46
	v_cvt_pk_bf16_f32 v106, v50, v54
	v_cvt_pk_bf16_f32 v107, v58, v62
	global_store_dwordx4 v126, v[104:107], s[48:49]
	s_add_u32 s48, s48, s53
	s_addc_u32 s49, s49, 0
	v_cvt_pk_bf16_f32 v108, v35, v39
	v_cvt_pk_bf16_f32 v109, v43, v47
	v_cvt_pk_bf16_f32 v110, v51, v55
	v_cvt_pk_bf16_f32 v111, v59, v63
	global_store_dwordx4 v126, v[108:111], s[48:49]
	s_add_u32 s48, s48, s53
	s_addc_u32 s49, s49, 0
	v_cvt_pk_bf16_f32 v104, v36, v40
	v_cvt_pk_bf16_f32 v105, v44, v48
	v_cvt_pk_bf16_f32 v106, v52, v56
	v_cvt_pk_bf16_f32 v107, v60, v64
	global_store_dwordx4 v126, v[104:107], s[48:49]
	s_add_u32 s48, s48, s53
	s_addc_u32 s49, s49, 0
	v_cvt_pk_bf16_f32 v108, v37, v41
	v_cvt_pk_bf16_f32 v109, v45, v49
	v_cvt_pk_bf16_f32 v110, v53, v57
	v_cvt_pk_bf16_f32 v111, v61, v65
	global_store_dwordx4 v126, v[108:111], s[48:49]
	s_mov_b64 exec, -1
	s_add_u32 s2, s2, 1
	s_sub_u32 s3, s3, 1
	s_cmp_lt_u32 s0, 12976
	s_cbranch_scc0 .Lcv_loop2
	s_cmp_lt_u32 s0, 1408
	s_cbranch_scc1 .Lcv_r1_m0
	s_cmp_lt_u32 s0, 2816
	s_cbranch_scc1 .Lcv_r1_m1
	s_cmp_lt_u32 s0, 4224
	s_cbranch_scc1 .Lcv_r1_m2
	s_cmp_lt_u32 s0, 7088
	s_cbranch_scc1 .Lcv_r1_m3
	s_cmp_lt_u32 s0, 7344
	s_cbranch_scc1 .Lcv_r1_m4
	s_cmp_lt_u32 s0, 7600
	s_cbranch_scc1 .Lcv_r1_m5
	s_cmp_lt_u32 s0, 8112
	s_cbranch_scc1 .Lcv_r1_m6
	s_cmp_lt_u32 s0, 9520
	s_cbranch_scc1 .Lcv_r1_m7
	s_cmp_lt_u32 s0, 10928
	s_cbranch_scc1 .Lcv_r1_m8
	s_cmp_lt_u32 s0, 12336
	s_cbranch_scc1 .Lcv_r1_m9
	s_cmp_lt_u32 s0, 12848
	s_cbranch_scc1 .Lcv_r1_m10
	s_movk_i32 s9, 0x100
	s_movk_i32 s10, 0x400
	s_movk_i32 s11, 32
	s_mov_b32 s12, 32768
	s_movk_i32 s13, 0x98
	s_mov_b32 s14, 0x100000
	s_mov_b32 s15, 0x3280000
	s_mov_b32 s16, 0
	s_movk_i32 s17, 12848
	s_branch .Lcv_r1_common

.Lcv_r1_common:
	s_sub_u32 s17, s0, s17
	s_load_dwordx2 s[20:21], s[4:5], s13
	s_mul_i32 s18, s17, s12
	s_lshr_b32 s18, s18, 20
	s_mul_i32 s19, s18, s11
	s_sub_u32 s19, s17, s19
	s_lshl_b32 s22, s19, 5
	s_sub_u32 s23, s10, s22
	s_lshr_b32 s23, s23, 2
	s_min_u32 s23, s23, 8
	v_cmp_gt_u32_e64 s[40:41], s23, v120
	s_mul_i32 s24, s18, s10
	s_lshl_b32 s24, s24, 6
	s_add_u32 s24, s24, s22
	s_lshl_b32 s24, s24, 2
	s_mul_i32 s25, s8, s14
	s_add_u32 s24, s24, s25
	s_lshl_b32 s25, s10, 5
	v_mad_u32_u24 v124, v121, s25, v122
	s_lshl_b32 s25, s10, 2
	s_waitcnt lgkmcnt(0)
	s_add_u32 s20, s20, s24
	s_addc_u32 s21, s21, 0
	s_mov_b64 exec, s[40:41]
	global_load_dwordx4 v[34:37], v124, s[20:21]
	s_add_u32 s20, s20, s25
	s_addc_u32 s21, s21, 0
	global_load_dwordx4 v[38:41], v124, s[20:21]
	s_add_u32 s20, s20, s25
	s_addc_u32 s21, s21, 0
	global_load_dwordx4 v[42:45], v124, s[20:21]
	s_add_u32 s20, s20, s25
	s_addc_u32 s21, s21, 0
	global_load_dwordx4 v[46:49], v124, s[20:21]
	s_add_u32 s20, s20, s25
	s_addc_u32 s21, s21, 0
	global_load_dwordx4 v[50:53], v124, s[20:21]
	s_add_u32 s20, s20, s25
	s_addc_u32 s21, s21, 0
	global_load_dwordx4 v[54:57], v124, s[20:21]
	s_add_u32 s20, s20, s25
	s_addc_u32 s21, s21, 0
	global_load_dwordx4 v[58:61], v124, s[20:21]
	s_add_u32 s20, s20, s25
	s_addc_u32 s21, s21, 0
	global_load_dwordx4 v[62:65], v124, s[20:21]
	s_mov_b64 exec, -1
	s_lshr_b32 s23, s22, 7
	s_lshl_b32 s23, s23, 8
	s_and_b32 s25, s22, 0x7f
	s_add_u32 s23, s23, s25
	s_cmp_eq_u32 s16, 0
	s_cselect_b32 s23, s22, s23
	s_cmp_eq_u32 s16, 2
	s_cselect_b32 s25, 0x80, 0
	s_add_u32 s23, s23, s25
	s_mul_i32 s23, s23, s9
	s_lshl_b32 s25, s18, 6
	s_add_u32 s23, s23, s25
	s_lshl_b32 s23, s23, 1
	s_add_u32 s23, s23, s15
	s_add_u32 s48, s6, s23
	s_addc_u32 s49, s7, 0
	s_lshl_b32 s53, s9, 1
	s_lshl_b32 s25, s9, 3
	v_mad_u32_u24 v126, v120, s25, v123
	s_add_u32 s0, s0, s76
	s_add_u32 s3, s3, 1
	s_branch .Lcv_loop2

.Lcv_l2_wd:
	s_mov_b64 exec, s[44:45]
	v_cvt_pk_bf16_f32 v104, v70, v74
	v_cvt_pk_bf16_f32 v105, v78, v82
	v_cvt_pk_bf16_f32 v106, v86, v90
	v_cvt_pk_bf16_f32 v107, v94, v98
	global_store_dwordx4 v127, v[104:107], s[50:51]
	s_add_u32 s50, s50, s54
	s_addc_u32 s51, s51, 0
	v_cvt_pk_bf16_f32 v108, v71, v75
	v_cvt_pk_bf16_f32 v109, v79, v83
	v_cvt_pk_bf16_f32 v110, v87, v91
	v_cvt_pk_bf16_f32 v111, v95, v99
	global_store_dwordx4 v127, v[108:111], s[50:51]
	s_add_u32 s50, s50, s54
	s_addc_u32 s51, s51, 0
	v_cvt_pk_bf16_f32 v104, v72, v76
	v_cvt_pk_bf16_f32 v105, v80, v84
	v_cvt_pk_bf16_f32 v106, v88, v92
	v_cvt_pk_bf16_f32 v107, v96, v100
	global_store_dwordx4 v127, v[104:107], s[50:51]
	s_add_u32 s50, s50, s54
	s_addc_u32 s51, s51, 0
	v_cvt_pk_bf16_f32 v108, v73, v77
	v_cvt_pk_bf16_f32 v109, v81, v85
	v_cvt_pk_bf16_f32 v110, v89, v93
	v_cvt_pk_bf16_f32 v111, v97, v101
	global_store_dwordx4 v127, v[108:111], s[50:51]
	s_mov_b64 exec, -1
	s_add_u32 s2, s2, 1
	s_sub_u32 s3, s3, 1
	s_cmp_lt_u32 s0, 12976
	s_cbranch_scc0 .Lcv_loop0
	s_cmp_lt_u32 s0, 1408
	s_cbranch_scc1 .Lcv_r2_m0
	s_cmp_lt_u32 s0, 2816
	s_cbranch_scc1 .Lcv_r2_m1
	s_cmp_lt_u32 s0, 4224
	s_cbranch_scc1 .Lcv_r2_m2
	s_cmp_lt_u32 s0, 7088
	s_cbranch_scc1 .Lcv_r2_m3
	s_cmp_lt_u32 s0, 7344
	s_cbranch_scc1 .Lcv_r2_m4
	s_cmp_lt_u32 s0, 7600
	s_cbranch_scc1 .Lcv_r2_m5
	s_cmp_lt_u32 s0, 8112
	s_cbranch_scc1 .Lcv_r2_m6
	s_cmp_lt_u32 s0, 9520
	s_cbranch_scc1 .Lcv_r2_m7
	s_cmp_lt_u32 s0, 10928
	s_cbranch_scc1 .Lcv_r2_m8
	s_cmp_lt_u32 s0, 12336
	s_cbranch_scc1 .Lcv_r2_m9
	s_cmp_lt_u32 s0, 12848
	s_cbranch_scc1 .Lcv_r2_m10
	s_movk_i32 s9, 0x100
	s_movk_i32 s10, 0x400
	s_movk_i32 s11, 32
	s_mov_b32 s12, 32768
	s_movk_i32 s13, 0x98
	s_mov_b32 s14, 0x100000
	s_mov_b32 s15, 0x3280000
	s_mov_b32 s16, 0
	s_movk_i32 s17, 12848
	s_branch .Lcv_r2_common

.Lcv_r2_common:
	s_sub_u32 s17, s0, s17
	s_load_dwordx2 s[20:21], s[4:5], s13
	s_mul_i32 s18, s17, s12
	s_lshr_b32 s18, s18, 20
	s_mul_i32 s19, s18, s11
	s_sub_u32 s19, s17, s19
	s_lshl_b32 s22, s19, 5
	s_sub_u32 s23, s10, s22
	s_lshr_b32 s23, s23, 2
	s_min_u32 s23, s23, 8
	v_cmp_gt_u32_e64 s[44:45], s23, v120
	s_mul_i32 s24, s18, s10
	s_lshl_b32 s24, s24, 6
	s_add_u32 s24, s24, s22
	s_lshl_b32 s24, s24, 2
	s_mul_i32 s25, s8, s14
	s_add_u32 s24, s24, s25
	s_lshl_b32 s25, s10, 5
	v_mad_u32_u24 v124, v121, s25, v122
	s_lshl_b32 s25, s10, 2
	s_waitcnt lgkmcnt(0)
	s_add_u32 s20, s20, s24
	s_addc_u32 s21, s21, 0
	s_mov_b64 exec, s[44:45]
	global_load_dwordx4 v[70:73], v124, s[20:21]
	s_add_u32 s20, s20, s25
	s_addc_u32 s21, s21, 0
	global_load_dwordx4 v[74:77], v124, s[20:21]
	s_add_u32 s20, s20, s25
	s_addc_u32 s21, s21, 0
	global_load_dwordx4 v[78:81], v124, s[20:21]
	s_add_u32 s20, s20, s25
	s_addc_u32 s21, s21, 0
	global_load_dwordx4 v[82:85], v124, s[20:21]
	s_add_u32 s20, s20, s25
	s_addc_u32 s21, s21, 0
	global_load_dwordx4 v[86:89], v124, s[20:21]
	s_add_u32 s20, s20, s25
	s_addc_u32 s21, s21, 0
	global_load_dwordx4 v[90:93], v124, s[20:21]
	s_add_u32 s20, s20, s25
	s_addc_u32 s21, s21, 0
	global_load_dwordx4 v[94:97], v124, s[20:21]
	s_add_u32 s20, s20, s25
	s_addc_u32 s21, s21, 0
	global_load_dwordx4 v[98:101], v124, s[20:21]
	s_mov_b64 exec, -1
	s_lshr_b32 s23, s22, 7
	s_lshl_b32 s23, s23, 8
	s_and_b32 s25, s22, 0x7f
	s_add_u32 s23, s23, s25
	s_cmp_eq_u32 s16, 0
	s_cselect_b32 s23, s22, s23
	s_cmp_eq_u32 s16, 2
	s_cselect_b32 s25, 0x80, 0
	s_add_u32 s23, s23, s25
	s_mul_i32 s23, s23, s9
	s_lshl_b32 s25, s18, 6
	s_add_u32 s23, s23, s25
	s_lshl_b32 s23, s23, 1
	s_add_u32 s23, s23, s15
	s_add_u32 s50, s6, s23
	s_addc_u32 s51, s7, 0
	s_lshl_b32 s54, s9, 1
	s_lshl_b32 s25, s9, 3
	v_mad_u32_u24 v127, v120, s25, v123
	s_add_u32 s0, s0, s76
	s_add_u32 s3, s3, 1
	s_branch .Lcv_loop0
.Lcv_done:
	s_branch .LBB0_1472
